# gdnout fragment loads issued at item start; bpost paired row sums via DPP/permlane
# speedup vs baseline: 1.0076x; 1.0009x over previous
; DI int otid() { int t = (int)__builtin_amdgcn_workitem_id_x(); asm volatile("" : "+v"(t)); return t; }
; DI f32x4 mfma16(bf16x8 a, bf16x8 b, f32x4 c) { return __builtin_amdgcn_mfma_f32_16x16x32_bf16(a, b, c, 0, 0, 0); }
; DI void gdnout_item(const Params& p, int l, int item, float* red  ) {
;   const int tid = otid(), lane = tid & 63, wid = tid >> 6, lr = lane & 15, lq = lane >> 4;
;   const int n = item >> 2, h = item & 3, t0 = n * 64;
;   const bf16_t* Qp = (const bf16_t*)(p.ws + OFF_RC + 16 * MiB) + (size_t)item * 8192;
;   const bf16_t* ATp = (const bf16_t*)(p.ws + OFF_ATT) + (size_t)item * 4096;
;   const float* GCp = (const float*)(p.ws + OFF_GC) + (size_t)item * 64;
;   const bf16x8* SN = (const bf16x8*)(p.ws + OFF_HB);
;   const bf16x8* VN = (const bf16x8*)(p.ws + OFF_CQ + 16 * MiB);
;   const bf16_t* RZ = (const bf16_t*)(p.ws + OFF_RZ);
;   bf16_t* OC = (bf16_t*)(p.ws + OFF_CQ + 32 * MiB);
;   f32x4 O[4][2];
; #pragma unroll
;   for (int mi = 0; mi < 4; ++mi) { O[mi][0] = (f32x4){0.f, 0.f, 0.f, 0.f}; O[mi][1] = (f32x4){0.f, 0.f, 0.f, 0.f}; }
; #pragma unroll
;   for (int s = 0; s < 4; ++s) {
;     bf16x8 b0 = SN[(((size_t)item * 8 + 2 * wid) * 4 + s) * 64 + lane], b1 = SN[(((size_t)item * 8 + 2 * wid + 1) * 4 + s) * 64 + lane];
; #pragma unroll
;     for (int mi = 0; mi < 4; ++mi) {
;       bf16x8 aq = *(const bf16x8*)(Qp + (mi * 16 + lr) * 128 + s * 32 + lq * 8);
;       O[mi][0] = mfma16(aq, b0, O[mi][0]); O[mi][1] = mfma16(aq, b1, O[mi][1]);
;     }
;   }
; #pragma unroll
;   for (int mi = 0; mi < 4; ++mi) {
;     f32x4 g = *(const f32x4*)(GCp + mi * 16 + lq * 4);
; #pragma unroll
;     for (int r = 0; r < 4; ++r) { float e = __expf(g[r]); O[mi][0][r] *= e; O[mi][1][r] *= e; }
;   }
; #pragma unroll
;   for (int s2 = 0; s2 < 2; ++s2) {
;     bf16x8 b0 = VN[(((size_t)item * 8 + 2 * wid) * 2 + s2) * 64 + lane], b1 = VN[(((size_t)item * 8 + 2 * wid + 1) * 2 + s2) * 64 + lane];
; #pragma unroll
;     for (int mi = 0; mi < 4; ++mi) {
;       bf16x8 aa = *(const bf16x8*)(ATp + (mi * 16 + lr) * 64 + s2 * 32 + lq * 8);
;       O[mi][0] = mfma16(aa, b0, O[mi][0]); O[mi][1] = mfma16(aa, b1, O[mi][1]);
;     }
.LBB0_310:
	s_and_b64 vcc, exec, s[36:37]
	s_cbranch_vccz .LBB0_305
	s_ashr_i32 s31, s30, 31
	s_lshl_b64 s[38:39], s[30:31], 14
	s_lshl_b64 s[18:19], s[30:31], 13
	s_add_u32 s36, s5, s18
	v_mov_b32_e32 v65, v201
	s_addc_u32 s37, s6, s19
	s_lshl_b64 s[40:41], s[30:31], 8
	s_add_u32 s18, s9, s38
	v_ashrrev_i32_e32 v66, 6, v65
	s_addc_u32 s19, s10, s39
	v_lshlrev_b32_e32 v20, 1, v66
	s_lshl_b64 s[44:45], s[30:31], 15
	v_ashrrev_i32_e32 v21, 31, v20
	s_add_u32 s44, s7, s44
	v_and_b32_e32 v0, 63, v65
	v_and_b32_e32 v64, 15, v65
	v_lshlrev_b64 v[2:3], 12, v[20:21]
	s_addc_u32 s45, s8, s45
	v_and_b32_e32 v248, 63, v201
	v_lshrrev_b32_e32 v249, 6, v201
	v_lshlrev_b32_e32 v248, 4, v248
	v_lshl_add_u32 v96, v249, 13, v248
	v_lshl_add_u32 v246, v249, 12, v248
	v_and_b32_e32 v248, 15, v201
	v_bfe_u32 v249, v201, 4, 2
	v_lshlrev_b32_e32 v249, 4, v249
	v_lshl_add_u32 v247, v248, 7, v249
	v_lshl_add_u32 v97, v248, 8, v249
	s_add_u32 s98, s13, s38
	s_addc_u32 s99, s14, s39
	global_load_dwordx4 v[80:83], v96, s[44:45]
	global_load_dwordx4 v[84:87], v96, s[44:45] offset:1024
	global_load_dwordx4 v[88:91], v96, s[44:45] offset:2048
	global_load_dwordx4 v[92:95], v96, s[44:45] offset:3072
	v_add_u32_e32 v96, 0x1000, v96
	global_load_dwordx4 v[102:105], v96, s[44:45]
	global_load_dwordx4 v[106:109], v96, s[44:45] offset:1024
	global_load_dwordx4 v[110:113], v96, s[44:45] offset:2048
	global_load_dwordx4 v[114:117], v96, s[44:45] offset:3072
	global_load_dwordx4 v[118:121], v97, s[18:19]
	global_load_dwordx4 v[122:125], v97, s[18:19] offset:64
	global_load_dwordx4 v[126:129], v97, s[18:19] offset:128
	global_load_dwordx4 v[130:133], v97, s[18:19] offset:192
	v_add_u32_e32 v97, 0x1000, v97
	global_load_dwordx4 v[134:137], v97, s[18:19]
	global_load_dwordx4 v[138:141], v97, s[18:19] offset:64
	global_load_dwordx4 v[142:145], v97, s[18:19] offset:128
	global_load_dwordx4 v[146:149], v97, s[18:19] offset:192
	v_add_u32_e32 v97, 0x1000, v97
	global_load_dwordx4 v[150:153], v97, s[18:19]
	global_load_dwordx4 v[154:157], v97, s[18:19] offset:64
	global_load_dwordx4 v[158:161], v97, s[18:19] offset:128
	global_load_dwordx4 v[162:165], v97, s[18:19] offset:192
	v_add_u32_e32 v97, 0x1000, v97
	global_load_dwordx4 v[166:169], v97, s[18:19]
	global_load_dwordx4 v[170:173], v97, s[18:19] offset:64
	global_load_dwordx4 v[174:177], v97, s[18:19] offset:128
	global_load_dwordx4 v[178:181], v97, s[18:19] offset:192
	global_load_dwordx4 v[182:185], v246, s[98:99]
	global_load_dwordx4 v[186:189], v246, s[98:99] offset:1024
	global_load_dwordx4 v[190:193], v246, s[98:99] offset:2048
	global_load_dwordx4 v[194:197], v246, s[98:99] offset:3072
	global_load_dwordx4 v[202:205], v247, s[36:37]
	global_load_dwordx4 v[206:209], v247, s[36:37] offset:64
	global_load_dwordx4 v[210:213], v247, s[36:37] offset:2048
	global_load_dwordx4 v[214:217], v247, s[36:37] offset:2112
	v_add_u32_e32 v247, 0x1000, v247
	global_load_dwordx4 v[222:225], v247, s[36:37]
	global_load_dwordx4 v[228:231], v247, s[36:37] offset:64
	global_load_dwordx4 v[238:241], v247, s[36:37] offset:2048
	global_load_dwordx4 v[242:245], v247, s[36:37] offset:2112
	v_and_b32_e32 v54, 48, v65
	v_mov_b32_e32 v55, v1
	v_lshl_add_u64 v[2:3], s[44:45], 0, v[2:3]
	v_lshlrev_b32_e32 v0, 4, v0
	v_lshl_add_u64 v[12:13], s[18:19], 0, v[54:55]
	v_lshlrev_b32_e32 v8, 8, v64
	v_mov_b32_e32 v9, v1
	v_lshl_add_u64 v[10:11], v[2:3], 0, v[0:1]
	v_lshl_add_u64 v[6:7], v[12:13], 0, v[8:9]
	s_waitcnt vmcnt(0)
	v_mov_b64_e32 v[22:23], v[80:81]
	v_mov_b64_e32 v[24:25], v[82:83]
	s_nop 1
	v_mov_b64_e32 v[2:3], v[118:119]
	v_mov_b64_e32 v[4:5], v[120:121]
	s_nop 1
	v_add_co_u32_e32 v14, vcc, s59, v10
	v_lshlrev_b32_e32 v18, 7, v64
	s_nop 0
	v_addc_co_u32_e32 v15, vcc, 0, v11, vcc
	v_mov_b64_e32 v[26:27], v[102:103]
	v_mov_b64_e32 v[28:29], v[104:105]
	s_nop 1
	v_or_b32_e32 v56, 0x1000, v18
	v_or_b32_e32 v58, 0x1800, v18
	s_mov_b64 s[18:19], 0x80
	s_add_u32 s40, s11, s40
	s_addc_u32 s41, s12, s41
	v_lshlrev_b64 v[20:21], 11, v[20:21]
	v_mov_b32_e32 v19, v1
	v_mov_b32_e32 v57, v1
	v_mov_b32_e32 v59, v1
	s_waitcnt vmcnt(1)
	v_mfma_f32_16x16x32_bf16 v[30:33], v[2:5], v[22:25], 0
	s_waitcnt vmcnt(0)
	v_mfma_f32_16x16x32_bf16 v[34:37], v[2:5], v[26:29], 0
	v_or_b32_e32 v2, 0x1000, v8
	v_mov_b32_e32 v3, v1
	v_lshl_add_u64 v[4:5], v[12:13], 0, v[2:3]
	v_mov_b64_e32 v[38:39], v[134:135]
	v_mov_b64_e32 v[40:41], v[136:137]
	s_nop 1
	v_lshlrev_b32_e32 v4, 1, v56
	v_mov_b32_e32 v5, v1
	v_lshl_add_u64 v[8:9], v[12:13], 0, v[4:5]
	v_mov_b64_e32 v[46:47], v[150:151]
	v_mov_b64_e32 v[48:49], v[152:153]
	s_nop 1
	v_lshlrev_b32_e32 v8, 1, v58
	v_mov_b32_e32 v9, v1
	v_lshl_add_u64 v[16:17], v[12:13], 0, v[8:9]
	v_mov_b64_e32 v[68:69], v[166:167]
	v_mov_b64_e32 v[70:71], v[168:169]
	s_nop 1
	v_lshl_add_u64 v[16:17], v[12:13], 0, 64
	v_lshl_add_u64 v[60:61], v[16:17], 0, v[2:3]
	s_waitcnt vmcnt(2)
	v_mfma_f32_16x16x32_bf16 v[42:45], v[38:41], v[22:25], 0
	v_mfma_f32_16x16x32_bf16 v[38:41], v[38:41], v[26:29], 0
	s_waitcnt vmcnt(1)
	v_mfma_f32_16x16x32_bf16 v[50:53], v[46:49], v[22:25], 0
	v_mfma_f32_16x16x32_bf16 v[46:49], v[46:49], v[26:29], 0
	s_waitcnt vmcnt(0)
	v_mfma_f32_16x16x32_bf16 v[22:25], v[68:71], v[22:25], 0
	v_mfma_f32_16x16x32_bf16 v[26:29], v[68:71], v[26:29], 0
	v_mov_b64_e32 v[68:69], v[84:85]
	v_mov_b64_e32 v[70:71], v[86:87]
	s_nop 1
	v_mov_b64_e32 v[72:73], v[106:107]
	v_mov_b64_e32 v[74:75], v[108:109]
	s_nop 1
	v_mov_b64_e32 v[76:77], v[122:123]
	v_mov_b64_e32 v[78:79], v[124:125]
	s_nop 1
	s_waitcnt vmcnt(0)
; DI f32x4 mfma16(bf16x8 a, bf16x8 b, f32x4 c) { return __builtin_amdgcn_mfma_f32_16x16x32_bf16(a, b, c, 0, 0, 0); }
; DI void gdnout_item(const Params& p, int l, int item, float* red  ) {
;     ...
;   for (int s = 0; s < 4; ++s) {
;     bf16x8 b0 = SN[(((size_t)item * 8 + 2 * wid) * 4 + s) * 64 + lane], b1 = SN[(((size_t)item * 8 + 2 * wid + 1) * 4 + s) * 64 + lane];
; #pragma unroll
;     for (int mi = 0; mi < 4; ++mi) {
;       bf16x8 aq = *(const bf16x8*)(Qp + (mi * 16 + lr) * 128 + s * 32 + lq * 8);
;       O[mi][0] = mfma16(aq, b0, O[mi][0]); O[mi][1] = mfma16(aq, b1, O[mi][1]);
;     }
;   }
; #pragma unroll
;   for (int mi = 0; mi < 4; ++mi) {
;     f32x4 g = *(const f32x4*)(GCp + mi * 16 + lq * 4);
; #pragma unroll
;     for (int r = 0; r < 4; ++r) { float e = __expf(g[r]); O[mi][0][r] *= e; O[mi][1][r] *= e; }
;   }
	v_mfma_f32_16x16x32_bf16 v[30:33], v[76:79], v[68:71], v[30:33]
	v_mfma_f32_16x16x32_bf16 v[34:37], v[76:79], v[72:75], v[34:37]
	v_mov_b64_e32 v[76:77], v[138:139]
	v_mov_b64_e32 v[78:79], v[140:141]
	s_nop 1
	v_lshl_add_u64 v[60:61], v[16:17], 0, v[4:5]
	v_lshl_add_u64 v[16:17], v[16:17], 0, v[8:9]
	s_waitcnt vmcnt(0)
	v_mfma_f32_16x16x32_bf16 v[42:45], v[76:79], v[68:71], v[42:45]
	v_mfma_f32_16x16x32_bf16 v[38:41], v[76:79], v[72:75], v[38:41]
	v_mov_b64_e32 v[76:77], v[154:155]
	v_mov_b64_e32 v[78:79], v[156:157]
	s_nop 1
	s_waitcnt vmcnt(0)
	v_mfma_f32_16x16x32_bf16 v[50:53], v[76:79], v[68:71], v[50:53]
	v_mfma_f32_16x16x32_bf16 v[46:49], v[76:79], v[72:75], v[46:49]
	v_mov_b64_e32 v[76:77], v[170:171]
	v_mov_b64_e32 v[78:79], v[172:173]
	s_nop 1
	v_lshl_add_u64 v[16:17], v[12:13], 0, s[18:19]
	v_lshl_add_u64 v[60:61], v[16:17], 0, v[2:3]
	s_mov_b64 s[18:19], 0xc0
	s_waitcnt vmcnt(0)
	v_mfma_f32_16x16x32_bf16 v[22:25], v[76:79], v[68:71], v[22:25]
	v_mfma_f32_16x16x32_bf16 v[26:29], v[76:79], v[72:75], v[26:29]
	v_mov_b64_e32 v[68:69], v[88:89]
	v_mov_b64_e32 v[70:71], v[90:91]
	s_nop 1
	v_mov_b64_e32 v[72:73], v[110:111]
	v_mov_b64_e32 v[74:75], v[112:113]
	s_nop 1
	v_mov_b64_e32 v[76:77], v[126:127]
	v_mov_b64_e32 v[78:79], v[128:129]
	s_nop 1
	s_waitcnt vmcnt(0)
	v_mfma_f32_16x16x32_bf16 v[30:33], v[76:79], v[68:71], v[30:33]
	v_mfma_f32_16x16x32_bf16 v[34:37], v[76:79], v[72:75], v[34:37]
	v_mov_b64_e32 v[76:77], v[142:143]
	v_mov_b64_e32 v[78:79], v[144:145]
	s_nop 1
	v_lshl_add_u64 v[60:61], v[16:17], 0, v[4:5]
	v_lshl_add_u64 v[16:17], v[16:17], 0, v[8:9]
	s_waitcnt vmcnt(0)
	v_mfma_f32_16x16x32_bf16 v[42:45], v[76:79], v[68:71], v[42:45]
	v_mfma_f32_16x16x32_bf16 v[38:41], v[76:79], v[72:75], v[38:41]
	v_mov_b64_e32 v[76:77], v[158:159]
	v_mov_b64_e32 v[78:79], v[160:161]
	s_nop 1
	v_lshl_add_u64 v[60:61], v[12:13], 0, s[18:19]
	v_lshl_add_u64 v[2:3], v[60:61], 0, v[2:3]
	s_add_u32 s18, s13, s38
	s_addc_u32 s19, s14, s39
	v_lshl_add_u64 v[20:21], s[18:19], 0, v[20:21]
	s_waitcnt vmcnt(0)
	v_mfma_f32_16x16x32_bf16 v[50:53], v[76:79], v[68:71], v[50:53]
	v_mfma_f32_16x16x32_bf16 v[46:49], v[76:79], v[72:75], v[46:49]
	v_mov_b64_e32 v[76:77], v[174:175]
	v_mov_b64_e32 v[78:79], v[176:177]
	s_nop 1
	s_waitcnt vmcnt(0)
	v_mfma_f32_16x16x32_bf16 v[22:25], v[76:79], v[68:71], v[22:25]
	v_mov_b64_e32 v[68:69], v[92:93]
	v_mov_b64_e32 v[70:71], v[94:95]
	s_nop 1
	s_nop 0
	v_mov_b64_e32 v[14:15], v[114:115]
	v_mov_b64_e32 v[16:17], v[116:117]
	s_nop 1
	s_nop 0
	v_mov_b64_e32 v[10:11], v[130:131]
	v_mov_b64_e32 v[12:13], v[132:133]
	s_nop 1
	v_mfma_f32_16x16x32_bf16 v[26:29], v[76:79], v[72:75], v[26:29]
	s_waitcnt vmcnt(0)
	v_mfma_f32_16x16x32_bf16 v[30:33], v[10:13], v[68:71], v[30:33]
	v_mfma_f32_16x16x32_bf16 v[10:13], v[10:13], v[14:17], v[34:37]
	s_nop 2
	v_mov_b64_e32 v[34:35], v[146:147]
	v_mov_b64_e32 v[36:37], v[148:149]
	s_nop 1
	v_lshl_add_u64 v[2:3], v[60:61], 0, v[4:5]
	v_mov_b64_e32 v[2:3], v[162:163]
	v_mov_b64_e32 v[4:5], v[164:165]
	s_nop 1
	s_waitcnt vmcnt(1)
	v_mfma_f32_16x16x32_bf16 v[42:45], v[34:37], v[68:71], v[42:45]
	v_mfma_f32_16x16x32_bf16 v[34:37], v[34:37], v[14:17], v[38:41]
	s_waitcnt vmcnt(0)
	v_mfma_f32_16x16x32_bf16 v[38:41], v[2:5], v[68:71], v[50:53]
	v_mfma_f32_16x16x32_bf16 v[46:49], v[2:5], v[14:17], v[46:49]
	v_lshl_add_u64 v[2:3], v[60:61], 0, v[8:9]
	v_mov_b64_e32 v[2:3], v[178:179]
	v_mov_b64_e32 v[4:5], v[180:181]
	s_nop 1
	v_lshl_add_u64 v[60:61], s[36:37], 0, v[54:55]
	s_waitcnt vmcnt(0)
	v_mfma_f32_16x16x32_bf16 v[22:25], v[2:5], v[68:71], v[22:25]
	v_lshl_add_u64 v[50:51], v[20:21], 0, v[0:1]
	v_lshl_add_u64 v[72:73], v[60:61], 0, v[18:19]
	v_xor_b32_e32 v0, 1, v227
	v_mfma_f32_16x16x32_bf16 v[26:29], v[2:5], v[14:17], v[26:29]
	global_load_dwordx4 v[2:5], v54, s[40:41]
	s_waitcnt vmcnt(0)
	v_mul_f32_e32 v2, 0x3fb8aa3b, v2
	v_exp_f32_e32 v6, v2
	v_mul_f32_e32 v2, 0x3fb8aa3b, v3
	v_exp_f32_e32 v7, v2
	v_mul_f32_e32 v2, 0x3fb8aa3b, v4
	v_exp_f32_e32 v8, v2
	v_mul_f32_e32 v2, 0x3fb8aa3b, v5
	v_exp_f32_e32 v9, v2
	v_pk_mul_f32 v[2:3], v[30:31], v[6:7]
	v_pk_mul_f32 v[6:7], v[10:11], v[6:7]
	v_pk_mul_f32 v[4:5], v[32:33], v[8:9]
	v_pk_mul_f32 v[8:9], v[12:13], v[8:9]
	global_load_dwordx4 v[10:13], v54, s[40:41] offset:64
	global_load_dwordx4 v[30:33], v54, s[40:41] offset:128
	s_waitcnt vmcnt(1)
	v_mul_f32_e32 v10, 0x3fb8aa3b, v10
	v_exp_f32_e32 v14, v10
	v_mul_f32_e32 v10, 0x3fb8aa3b, v11
	v_exp_f32_e32 v15, v10
	v_mul_f32_e32 v10, 0x3fb8aa3b, v12
	v_exp_f32_e32 v16, v10
	v_mul_f32_e32 v10, 0x3fb8aa3b, v13
	v_exp_f32_e32 v17, v10
	s_waitcnt vmcnt(0)
; DI f32x4 mfma16(bf16x8 a, bf16x8 b, f32x4 c) { return __builtin_amdgcn_mfma_f32_16x16x32_bf16(a, b, c, 0, 0, 0); }
; DI void gdnout_item(const Params& p, int l, int item, float* red  ) {
;     ...
; #pragma unroll
;   for (int mi = 0; mi < 4; ++mi) {
;     f32x4 g = *(const f32x4*)(GCp + mi * 16 + lq * 4);
; #pragma unroll
;     for (int r = 0; r < 4; ++r) { float e = __expf(g[r]); O[mi][0][r] *= e; O[mi][1][r] *= e; }
;   }
; #pragma unroll
;   for (int s2 = 0; s2 < 2; ++s2) {
;     bf16x8 b0 = VN[(((size_t)item * 8 + 2 * wid) * 2 + s2) * 64 + lane], b1 = VN[(((size_t)item * 8 + 2 * wid + 1) * 2 + s2) * 64 + lane];
; #pragma unroll
;     for (int mi = 0; mi < 4; ++mi) {
;       bf16x8 aa = *(const bf16x8*)(ATp + (mi * 16 + lr) * 64 + s2 * 32 + lq * 8);
;       O[mi][0] = mfma16(aa, b0, O[mi][0]); O[mi][1] = mfma16(aa, b1, O[mi][1]);
;     }
;   }
;   __syncthreads();
; #pragma unroll
;   for (int mi = 0; mi < 4; ++mi)
; #pragma unroll
;     for (int r = 0; r < 4; ++r) {
;       float ss = O[mi][0][r] * O[mi][0][r] + O[mi][1][r] * O[mi][1][r];
;       ss += __shfl_xor(ss, 1); ss += __shfl_xor(ss, 2); ss += __shfl_xor(ss, 4); ss += __shfl_xor(ss, 8);
;       if (lr == 0) red[wid * 64 + mi * 16 + lq * 4 + r] = ss;
	v_mul_f32_e32 v30, 0x3fb8aa3b, v30
	v_pk_mul_f32 v[10:11], v[42:43], v[14:15]
	v_pk_mul_f32 v[14:15], v[34:35], v[14:15]
	v_exp_f32_e32 v34, v30
	v_mul_f32_e32 v30, 0x3fb8aa3b, v31
	v_exp_f32_e32 v35, v30
	v_mul_f32_e32 v30, 0x3fb8aa3b, v32
	v_pk_mul_f32 v[12:13], v[44:45], v[16:17]
	v_pk_mul_f32 v[16:17], v[36:37], v[16:17]
	v_exp_f32_e32 v36, v30
	v_mul_f32_e32 v30, 0x3fb8aa3b, v33
	v_exp_f32_e32 v37, v30
	v_pk_mul_f32 v[30:31], v[38:39], v[34:35]
	v_pk_mul_f32 v[34:35], v[46:47], v[34:35]
	v_pk_mul_f32 v[32:33], v[40:41], v[36:37]
	global_load_dwordx4 v[38:41], v54, s[40:41] offset:192
	v_pk_mul_f32 v[36:37], v[48:49], v[36:37]
	s_waitcnt vmcnt(0)
	v_mul_f32_e32 v38, 0x3fb8aa3b, v38
	v_mul_f32_e32 v39, 0x3fb8aa3b, v39
	v_mul_f32_e32 v40, 0x3fb8aa3b, v40
	v_mul_f32_e32 v41, 0x3fb8aa3b, v41
	v_exp_f32_e32 v38, v38
	v_exp_f32_e32 v39, v39
	v_exp_f32_e32 v40, v40
	v_exp_f32_e32 v41, v41
	v_pk_mul_f32 v[22:23], v[22:23], v[38:39]
	v_pk_mul_f32 v[26:27], v[26:27], v[38:39]
	v_pk_mul_f32 v[24:25], v[24:25], v[40:41]
	v_pk_mul_f32 v[28:29], v[28:29], v[40:41]
	v_mov_b64_e32 v[38:39], v[182:183]
	v_mov_b64_e32 v[40:41], v[184:185]
	s_nop 1
	v_mov_b64_e32 v[42:43], v[190:191]
	v_mov_b64_e32 v[44:45], v[192:193]
	s_nop 1
	v_mov_b64_e32 v[18:19], v[202:203]
	v_mov_b64_e32 v[20:21], v[204:205]
	s_nop 1
	s_waitcnt vmcnt(0)
	v_mfma_f32_16x16x32_bf16 v[68:71], v[18:21], v[38:41], v[2:5]
	v_mfma_f32_16x16x32_bf16 v[18:21], v[18:21], v[42:45], v[6:9]
	s_nop 2
	v_mov_b64_e32 v[6:7], v[210:211]
	v_mov_b64_e32 v[8:9], v[212:213]
	s_nop 1
	s_waitcnt vmcnt(0)
	v_mfma_f32_16x16x32_bf16 v[2:5], v[6:9], v[38:41], v[10:13]
	s_nop 2
	v_lshl_add_u64 v[10:11], v[60:61], 0, v[56:57]
	v_mfma_f32_16x16x32_bf16 v[6:9], v[6:9], v[42:45], v[14:17]
	s_nop 2
	v_mov_b64_e32 v[14:15], v[222:223]
	v_mov_b64_e32 v[16:17], v[224:225]
	s_nop 1
	s_waitcnt vmcnt(0)
	v_mfma_f32_16x16x32_bf16 v[10:13], v[14:17], v[38:41], v[30:33]
	v_mfma_f32_16x16x32_bf16 v[34:37], v[14:17], v[42:45], v[34:37]
	v_lshl_add_u64 v[14:15], v[60:61], 0, v[58:59]
	v_mov_b64_e32 v[14:15], v[238:239]
	v_mov_b64_e32 v[16:17], v[240:241]
	s_nop 1
	s_nop 0
	v_mov_b64_e32 v[46:47], v[186:187]
	v_mov_b64_e32 v[48:49], v[188:189]
	s_nop 1
	s_nop 0
	v_mov_b64_e32 v[50:51], v[194:195]
	v_mov_b64_e32 v[52:53], v[196:197]
	s_nop 1
	s_waitcnt vmcnt(2)
	v_mfma_f32_16x16x32_bf16 v[38:41], v[14:17], v[38:41], v[22:25]
	v_lshl_add_u64 v[60:61], v[60:61], 0, 64
	v_mfma_f32_16x16x32_bf16 v[42:45], v[14:17], v[42:45], v[26:29]
	v_mov_b64_e32 v[14:15], v[206:207]
	v_mov_b64_e32 v[16:17], v[208:209]
	s_nop 1
	s_waitcnt vmcnt(0)
	v_mfma_f32_16x16x32_bf16 v[30:33], v[14:17], v[46:49], v[68:71]
	v_mfma_f32_16x16x32_bf16 v[26:29], v[14:17], v[50:53], v[18:21]
	v_mov_b64_e32 v[14:15], v[214:215]
	v_mov_b64_e32 v[16:17], v[216:217]
	s_nop 1
	s_waitcnt vmcnt(0)
	v_mfma_f32_16x16x32_bf16 v[22:25], v[14:17], v[46:49], v[2:5]
	s_nop 2
	v_lshl_add_u64 v[2:3], v[60:61], 0, v[56:57]
	v_mov_b64_e32 v[2:3], v[228:229]
	v_mov_b64_e32 v[4:5], v[230:231]
	s_nop 1
	v_mfma_f32_16x16x32_bf16 v[18:21], v[14:17], v[50:53], v[6:9]
	s_waitcnt vmcnt(0)
	v_mfma_f32_16x16x32_bf16 v[14:17], v[2:5], v[46:49], v[10:13]
	v_mfma_f32_16x16x32_bf16 v[10:13], v[2:5], v[50:53], v[34:37]
	v_lshl_add_u64 v[2:3], v[60:61], 0, v[58:59]
	v_mov_b64_e32 v[2:3], v[242:243]
	v_mov_b64_e32 v[4:5], v[244:245]
	s_nop 1
	s_nop 0
	v_and_b32_e32 v34, 64, v227
	v_add_u32_e32 v34, 64, v34
	v_cmp_lt_i32_e32 vcc, v0, v34
	s_waitcnt vmcnt(0)
	v_mfma_f32_16x16x32_bf16 v[6:9], v[2:5], v[46:49], v[38:41]
	v_cndmask_b32_e32 v0, v227, v0, vcc
	s_nop 1
	v_mul_f32_e32 v38, v26, v26
	v_lshlrev_b32_e32 v0, 2, v0
	v_fmac_f32_e32 v38, v30, v30
	s_nop 1
	v_add_f32_dpp v38, v38, v38 quad_perm:[1,0,3,2] row_mask:0xf bank_mask:0xf
	v_xor_b32_e32 v35, 2, v227
	v_cmp_lt_i32_e32 vcc, v35, v34
	v_xor_b32_e32 v36, 4, v227
	v_xor_b32_e32 v37, 8, v227
	v_cndmask_b32_e32 v35, v227, v35, vcc
	v_lshlrev_b32_e32 v35, 2, v35
	s_waitcnt lgkmcnt(0)
	s_nop 1
	v_add_f32_dpp v38, v38, v38 quad_perm:[2,3,0,1] row_mask:0xf bank_mask:0xf
	v_cmp_lt_i32_e32 vcc, v36, v34
	v_mfma_f32_16x16x32_bf16 v[2:5], v[2:5], v[50:53], v[42:45]
	s_barrier
	v_cndmask_b32_e32 v36, v227, v36, vcc
	v_lshlrev_b32_e32 v36, 2, v36
	s_waitcnt lgkmcnt(0)
	s_nop 1
	v_add_f32_dpp v38, v38, v38 row_half_mirror row_mask:0xf bank_mask:0xf
	v_cmp_lt_i32_e32 vcc, v37, v34
	s_waitcnt lgkmcnt(0)
	v_cndmask_b32_e32 v34, v227, v37, vcc
	v_lshlrev_b32_e32 v37, 2, v34
	s_nop 1
	v_add_f32_dpp v38, v38, v38 row_mirror row_mask:0xf bank_mask:0xf
	v_and_b32_e32 v34, 0x3fffffc0, v65
	v_cmp_eq_u32_e32 vcc, 0, v64
	v_lshlrev_b32_e32 v34, 2, v34
	s_and_saveexec_b64 s[36:37], vcc
	s_cbranch_execz .LBB0_313
	s_waitcnt lgkmcnt(0)
	v_add_u32_e32 v39, v34, v54
	ds_write_b32 v39, v38

; DI float bf2f(unsigned h) { return __uint_as_float(h << 16); }
; DI void bpost_item(const Params& p, int l, int b, int item, bf16_t* lds) {
;     ...
;   for (int rr = 0; rr < 4; ++rr) {
;     const int t = t0 + wid * 4 + rr;
;     float ssq = 0.f, sskv = 0.f;
;     {
;       const bf16_t* q = RB + (size_t)t * 768;
; #pragma unroll
;       for (int j = 0; j < 6; ++j) { float v = bf2f(q[lane + 64 * j]); ssq += v * v; }
; #pragma unroll
;       for (int j = 0; j < 4; ++j) { float v = bf2f(q[384 + lane + 64 * j]); sskv += v * v; }
;     }
;     ssq = wave_sum(ssq); sskv = wave_sum(sskv);
;     const float rq = rsqrtf(ssq * (1.f / 384.f) + EPS), rkv = rsqrtf(sskv * (1.f / 256.f) + EPS);
;     if (lane == 0) srs[wid * 4 + rr] = rkv;
;     const float ang = (float)p.pos[(size_t)b * TT + t] * invf;
;     float sn, cs; sincosf(ang, &sn, &cs);
.LBB0_453:
	v_mad_i64_i32 v[22:23], s[0:1], v14, s86, 0
	v_lshl_add_u64 v[18:19], v[22:23], 1, v[10:11]
	global_load_ushort v0, v[18:19], off offset:384
	global_load_ushort v15, v[18:19], off offset:768
	global_load_ushort v20, v[18:19], off offset:512
	s_waitcnt lgkmcnt(0)
	global_load_ushort v16, v[18:19], off offset:256
	global_load_ushort v21, v[18:19], off offset:640
	global_load_ushort v24, v[18:19], off offset:896
	global_load_ushort v26, v[18:19], off offset:1152
	global_load_ushort v38, v[18:19], off offset:1024
	global_load_ushort v39, v[18:19], off offset:128
	global_load_ushort v40, v[18:19], off
	s_waitcnt vmcnt(9)
	v_lshlrev_b32_e32 v17, 16, v0
	s_waitcnt vmcnt(7)
	v_lshlrev_b32_e32 v20, 16, v20
	s_waitcnt vmcnt(6)
	v_lshlrev_b32_e32 v16, 16, v16
	s_waitcnt vmcnt(5)
	v_lshlrev_b32_e32 v21, 16, v21
	s_waitcnt vmcnt(4)
	v_lshlrev_b32_e32 v25, 16, v24
	s_waitcnt vmcnt(3)
	v_lshlrev_b32_e32 v27, 16, v26
	s_waitcnt vmcnt(2)
	v_lshlrev_b32_e32 v26, 16, v38
	s_waitcnt vmcnt(1)
	v_lshlrev_b32_e32 v39, 16, v39
	s_waitcnt vmcnt(0)
	v_lshlrev_b32_e32 v38, 16, v40
	v_mul_f32_e32 v0, v39, v39
	v_lshlrev_b32_e32 v24, 16, v15
	v_pk_fma_f32 v[38:39], v[38:39], v[38:39], v[0:1] op_sel_hi:[1,1,0]
	v_pk_mul_f32 v[40:41], v[16:17], v[16:17]
	v_pk_mul_f32 v[24:25], v[24:25], v[24:25]
	v_pk_fma_f32 v[16:17], v[16:17], v[16:17], v[38:39]
	v_pk_mul_f32 v[20:21], v[20:21], v[20:21]
	v_pk_mul_f32 v[26:27], v[26:27], v[26:27]
	v_mov_b32_e32 v40, v25
	v_mov_b32_e32 v25, v16
	v_mov_b32_e32 v42, v26
	v_mov_b32_e32 v43, v20
	v_pk_add_f32 v[16:17], v[24:25], v[40:41]
	v_mov_b32_e32 v20, v27
	v_pk_add_f32 v[16:17], v[16:17], v[42:43]
	s_nop 0
	v_pk_add_f32 v[16:17], v[16:17], v[20:21]
	s_nop 1
	v_add_f32_dpp v16, v16, v16 quad_perm:[1,0,3,2] row_mask:0xf bank_mask:0xf
	v_add_f32_dpp v17, v17, v17 quad_perm:[1,0,3,2] row_mask:0xf bank_mask:0xf
	s_nop 1
	v_add_f32_dpp v16, v16, v16 quad_perm:[2,3,0,1] row_mask:0xf bank_mask:0xf
	v_add_f32_dpp v17, v17, v17 quad_perm:[2,3,0,1] row_mask:0xf bank_mask:0xf
	s_nop 1
	v_add_f32_dpp v16, v16, v16 row_half_mirror row_mask:0xf bank_mask:0xf
	v_add_f32_dpp v17, v17, v17 row_half_mirror row_mask:0xf bank_mask:0xf
	s_nop 1
	v_add_f32_dpp v16, v16, v16 row_mirror row_mask:0xf bank_mask:0xf
	v_add_f32_dpp v17, v17, v17 row_mirror row_mask:0xf bank_mask:0xf
	v_mov_b32_e32 v20, v16
	v_mov_b32_e32 v21, v17
	s_nop 1
	v_permlane16_swap_b32_e32 v16, v20
	v_permlane16_swap_b32_e32 v17, v21
	s_nop 1
	v_add_f32_e32 v16, v16, v20
	v_add_f32_e32 v17, v17, v21
	v_mov_b32_e32 v20, v16
	v_mov_b32_e32 v21, v17
	s_nop 1
	v_permlane32_swap_b32_e32 v16, v20
	v_permlane32_swap_b32_e32 v17, v21
	s_nop 1
	v_add_f32_e32 v16, v16, v20
	v_add_f32_e32 v17, v17, v21
	s_nop 0
	v_pk_fma_f32 v[16:17], v[16:17], s[10:11], v[200:201] op_sel_hi:[1,1,0]
	s_nop 0
	v_mul_f32_e32 v0, 0x4b800000, v16
	v_cmp_gt_f32_e64 s[0:1], s58, v16
	v_cmp_gt_f32_e32 vcc, s58, v17
	s_nop 0
	v_cndmask_b32_e64 v0, v16, v0, s[0:1]
	v_rsq_f32_e32 v0, v0
	s_nop 0
	v_mul_f32_e32 v15, 0x45800000, v0
	v_cndmask_b32_e64 v38, v0, v15, s[0:1]
	s_and_saveexec_b64 s[0:1], s[38:39]
	v_add_u32_e32 v0, s4, v37
	ds_write_b32 v0, v38
	s_or_b64 exec, exec, s[0:1]
	v_ashrrev_i32_e32 v15, 31, v14
	v_lshl_add_u64 v[20:21], v[14:15], 2, s[22:23]
	global_load_dword v0, v[20:21], off
	s_brev_b32 s0, 18
	s_waitcnt vmcnt(0)
	v_cvt_f32_i32_e32 v0, v0
	v_mul_f32_e32 v15, v30, v0
	v_and_b32_e32 v26, 0x7fffffff, v15
	v_cmp_nlt_f32_e64 s[0:1], |v15|, s0
	s_and_saveexec_b64 s[6:7], s[0:1]
	s_xor_b64 s[24:25], exec, s[6:7]
	s_cbranch_execz .LBB0_457
	v_lshrrev_b32_e32 v0, 23, v26
	v_add_u32_e32 v0, 0xffffff88, v0
	v_cmp_lt_u32_e64 s[0:1], 63, v0
	v_not_b32_e32 v16, 63
	s_mov_b32 s5, 0xfe5163ab
	v_cndmask_b32_e64 v16, 0, v16, s[0:1]
	v_add_u32_e32 v0, v16, v0
	v_cmp_lt_u32_e64 s[44:45], 31, v0
	s_nop 1
	v_cndmask_b32_e64 v16, 0, v172, s[44:45]
	v_add_u32_e32 v0, v16, v0
	v_cmp_lt_u32_e64 s[46:47], 31, v0
	s_nop 1
	v_cndmask_b32_e64 v16, 0, v172, s[46:47]
	v_add_u32_e32 v16, v16, v0
	v_and_b32_e32 v0, 0x7fffff, v26
	v_or_b32_e32 v27, 0x800000, v0
	v_mad_u64_u32 v[20:21], s[6:7], v27, s5, 0
	v_mov_b32_e32 v0, v21
	s_mov_b32 s5, 0x3c439041
	v_mad_u64_u32 v[24:25], s[6:7], v27, s5, v[0:1]
	v_mov_b32_e32 v0, v25
	s_mov_b32 s5, 0xdb629599
	v_mad_u64_u32 v[40:41], s[6:7], v27, s5, v[0:1]
	v_mov_b32_e32 v0, v41
	s_mov_b32 s5, 0xf534ddc0
	v_mad_u64_u32 v[42:43], s[6:7], v27, s5, v[0:1]
	v_mov_b32_e32 v0, v43
	s_mov_b32 s5, 0xfc2757d1
	v_mad_u64_u32 v[44:45], s[6:7], v27, s5, v[0:1]
	v_mov_b32_e32 v0, v45
	s_mov_b32 s5, 0x4e441529
	v_mad_u64_u32 v[46:47], s[6:7], v27, s5, v[0:1]
	v_mov_b32_e32 v0, v47
	s_mov_b32 s5, 0xa2f9836e
	v_mad_u64_u32 v[48:49], s[6:7], v27, s5, v[0:1]
	v_cndmask_b32_e64 v21, v46, v42, s[0:1]
	v_cndmask_b32_e64 v0, v48, v44, s[0:1]
	v_cndmask_b32_e64 v27, v49, v46, s[0:1]
	v_cndmask_b32_e64 v25, v0, v21, s[44:45]
	v_cndmask_b32_e64 v0, v27, v0, s[44:45]
	v_cndmask_b32_e64 v27, v44, v40, s[0:1]
	v_cndmask_b32_e64 v21, v21, v27, s[44:45]
	v_cndmask_b32_e64 v0, v0, v25, s[46:47]
	v_cndmask_b32_e64 v25, v25, v21, s[46:47]
	v_sub_u32_e32 v39, 32, v16
	v_alignbit_b32 v41, v0, v25, v39
	v_cmp_eq_u32_e64 s[48:49], 0, v16
	v_cndmask_b32_e64 v20, v40, v20, s[0:1]
	s_nop 0
	v_cndmask_b32_e64 v16, v41, v0, s[48:49]
	v_cndmask_b32_e64 v0, v42, v24, s[0:1]
	v_cndmask_b32_e64 v24, v27, v0, s[44:45]
	v_cndmask_b32_e64 v21, v21, v24, s[46:47]
	v_alignbit_b32 v27, v25, v21, v39
	v_cndmask_b32_e64 v25, v27, v25, s[48:49]
	v_bfe_u32 v42, v16, 29, 1
	v_cndmask_b32_e64 v0, v0, v20, s[44:45]
	v_alignbit_b32 v27, v16, v25, 30
	v_sub_u32_e32 v43, 0, v42
	v_cndmask_b32_e64 v0, v24, v0, s[46:47]
	v_xor_b32_e32 v27, v27, v43
	v_alignbit_b32 v20, v21, v0, v39
	v_cndmask_b32_e64 v20, v20, v21, s[48:49]
	v_ffbh_u32_e32 v24, v27
	v_alignbit_b32 v21, v25, v20, 30
	v_min_u32_e32 v24, 32, v24
	v_alignbit_b32 v0, v20, v0, 30
	v_xor_b32_e32 v21, v21, v43
	v_sub_u32_e32 v25, 31, v24
	v_xor_b32_e32 v0, v0, v43
	v_alignbit_b32 v27, v27, v21, v25
	v_alignbit_b32 v0, v21, v0, v25
	v_alignbit_b32 v20, v27, v0, 9
	v_ffbh_u32_e32 v21, v20
	v_min_u32_e32 v21, 32, v21
	v_lshrrev_b32_e32 v41, 29, v16
	v_not_b32_e32 v25, v21
	v_alignbit_b32 v0, v20, v0, v25
	v_lshlrev_b32_e32 v20, 31, v41
	v_or_b32_e32 v25, 0x33000000, v20
	v_add_lshl_u32 v21, v21, v24, 23
	v_lshrrev_b32_e32 v0, 9, v0
	v_sub_u32_e32 v21, v25, v21
	v_or_b32_e32 v20, 0.5, v20
	v_lshlrev_b32_e32 v24, 23, v24
	v_or_b32_e32 v0, v21, v0
	v_lshrrev_b32_e32 v21, 9, v27
	v_sub_u32_e32 v20, v20, v24
	v_or_b32_e32 v20, v21, v20
	v_mul_f32_e32 v21, 0x3fc90fda, v20
	s_mov_b32 s0, 0x3fc90fda
	v_fma_f32 v24, v20, s0, -v21
	v_fmac_f32_e32 v24, 0x33a22168, v20
	v_fmac_f32_e32 v24, 0x3fc90fda, v0
	v_lshrrev_b32_e32 v16, 30, v16
	v_add_f32_e32 v0, v21, v24
	v_add_u32_e32 v27, v42, v16
